# GEMM phases: the dead 'next unit' prefetch of a workgroup's last unit re-reads the two K tiles just consumed (L2-hot) instead of the unit's cold tiles 0/1
# speedup vs baseline: 1.0065x; 1.0061x over previous
; template <class Epi, class Sched, bool ALIGN_EPI = false, bool SP2 = false>
; __device__ __forceinline__ void gemm_phase(PG8_LAS unsigned char* lds, const Gemm g, const Sched& S, const Epi& E, const int tid) {
;     ...
;         const bool has_next = S.next(ui + 1, nxt);
;         const char* nA = has_next ? (const char*)g.A + (size_t)nxt.pm * tstep : cA; const char* nB = has_next ? (const char*)g.Bt + (size_t)nxt.pn * tstep : cB;
;     ...
; #pragma unroll
;         for (int a = 0; a < 2; ++a)
; #pragma unroll
;             for (int b = 0; b < 2; ++b)
; #pragma unroll
;                 for (int m = 0; m < 4; ++m)
; #pragma unroll
;                     for (int n = 0; n < 2; ++n) acc[a][b][m][n] = (f32x4){0.f, 0.f, 0.f, 0.f};
.LBB0_210:
	s_ashr_i32 s49, s48, 31
	s_lshl_b64 s[50:51], s[48:49], 20
	s_add_u32 s50, s2, s50
	s_addc_u32 s51, s36, s51
	s_and_b64 s[52:53], s[40:41], exec
	s_cselect_b32 s49, s51, s57
	s_cselect_b32 s72, s50, s56
	s_ashr_i32 s47, s46, 31
	s_lshl_b64 s[52:53], s[46:47], 20
	s_add_u32 s52, s38, s52
	s_addc_u32 s53, s39, s53
	s_and_b64 s[58:59], s[40:41], exec
	s_cselect_b32 s47, s53, s55
	s_cselect_b32 s73, s52, s54
	s_cselect_b32 s100, 0, 0xf00
	s_add_u32 s72, s72, s100
	s_addc_u32 s49, s49, 0
	s_add_u32 s73, s73, s100
	s_addc_u32 s47, s47, 0
	s_add_u32 s75, s54, 0x100
	s_addc_u32 s76, s55, 0
	s_add_u32 s54, s56, 0x80080
	v_mov_b32_e32 v0, 0
	s_addc_u32 s55, s57, 0
	s_mov_b32 s77, -2
	v_mov_b32_e32 v1, v0
	v_mov_b32_e32 v2, v0
	v_mov_b32_e32 v3, v0
	v_mov_b32_e32 v8, v0
	v_mov_b32_e32 v9, v0
	v_mov_b32_e32 v10, v0
	v_mov_b32_e32 v11, v0
	v_mov_b32_e32 v16, v0
	v_mov_b32_e32 v17, v0
	v_mov_b32_e32 v18, v0
	v_mov_b32_e32 v19, v0
	v_mov_b32_e32 v24, v0
	v_mov_b32_e32 v25, v0
	v_mov_b32_e32 v26, v0
	v_mov_b32_e32 v27, v0
	v_mov_b32_e32 v32, v0
	v_mov_b32_e32 v33, v0
	v_mov_b32_e32 v34, v0
	v_mov_b32_e32 v35, v0
	v_mov_b32_e32 v40, v0
	v_mov_b32_e32 v41, v0
	v_mov_b32_e32 v42, v0
	v_mov_b32_e32 v43, v0
	v_mov_b32_e32 v48, v0
	v_mov_b32_e32 v49, v0
	v_mov_b32_e32 v50, v0
	v_mov_b32_e32 v51, v0
	v_mov_b32_e32 v56, v0
	v_mov_b32_e32 v57, v0
	v_mov_b32_e32 v58, v0
	v_mov_b32_e32 v59, v0
	v_mov_b32_e32 v4, v0
	v_mov_b32_e32 v5, v0
	v_mov_b32_e32 v6, v0
	v_mov_b32_e32 v7, v0
	v_mov_b32_e32 v12, v0
	v_mov_b32_e32 v13, v0
	v_mov_b32_e32 v14, v0
	v_mov_b32_e32 v15, v0
	v_mov_b32_e32 v20, v0
	v_mov_b32_e32 v21, v0
	v_mov_b32_e32 v22, v0
	v_mov_b32_e32 v23, v0
	v_mov_b32_e32 v28, v0
	v_mov_b32_e32 v29, v0
	v_mov_b32_e32 v30, v0
	v_mov_b32_e32 v31, v0
	v_mov_b32_e32 v36, v0
	v_mov_b32_e32 v37, v0
	v_mov_b32_e32 v38, v0
	v_mov_b32_e32 v39, v0
	v_mov_b32_e32 v44, v0
	v_mov_b32_e32 v45, v0
	v_mov_b32_e32 v46, v0
	v_mov_b32_e32 v47, v0
	v_mov_b32_e32 v52, v0
	v_mov_b32_e32 v53, v0
	v_mov_b32_e32 v54, v0
	v_mov_b32_e32 v55, v0
	v_mov_b32_e32 v60, v0
	v_mov_b32_e32 v61, v0
	v_mov_b32_e32 v62, v0
	v_mov_b32_e32 v63, v0
	v_mov_b32_e32 v64, v0
	v_mov_b32_e32 v65, v0
	v_mov_b32_e32 v66, v0
	v_mov_b32_e32 v67, v0
	v_mov_b32_e32 v72, v0
	v_mov_b32_e32 v73, v0
	v_mov_b32_e32 v74, v0
	v_mov_b32_e32 v75, v0
	v_mov_b32_e32 v80, v0
	v_mov_b32_e32 v81, v0
	v_mov_b32_e32 v82, v0
	v_mov_b32_e32 v83, v0
	v_mov_b32_e32 v88, v0
	v_mov_b32_e32 v89, v0
	v_mov_b32_e32 v90, v0
	v_mov_b32_e32 v91, v0
	v_mov_b32_e32 v102, v0
	v_mov_b32_e32 v103, v0
	v_mov_b32_e32 v104, v0
	v_mov_b32_e32 v105, v0
	v_mov_b32_e32 v110, v0
	v_mov_b32_e32 v111, v0
	v_mov_b32_e32 v112, v0
	v_mov_b32_e32 v113, v0
	v_mov_b32_e32 v118, v0
	v_mov_b32_e32 v119, v0
	v_mov_b32_e32 v120, v0
	v_mov_b32_e32 v121, v0
	v_mov_b32_e32 v122, v0
	v_mov_b32_e32 v123, v0
	v_mov_b32_e32 v124, v0
	v_mov_b32_e32 v125, v0
	v_mov_b32_e32 v68, v0
	v_mov_b32_e32 v69, v0
	v_mov_b32_e32 v70, v0
	v_mov_b32_e32 v71, v0
	v_mov_b32_e32 v76, v0
	v_mov_b32_e32 v77, v0
	v_mov_b32_e32 v78, v0
	v_mov_b32_e32 v79, v0
	v_mov_b32_e32 v84, v0
	v_mov_b32_e32 v85, v0
	v_mov_b32_e32 v86, v0
	v_mov_b32_e32 v87, v0
	v_mov_b32_e32 v92, v0
	v_mov_b32_e32 v93, v0
	v_mov_b32_e32 v94, v0
	v_mov_b32_e32 v95, v0
	v_mov_b32_e32 v106, v0
	v_mov_b32_e32 v107, v0
	v_mov_b32_e32 v108, v0
	v_mov_b32_e32 v109, v0
	v_mov_b32_e32 v114, v0
	v_mov_b32_e32 v115, v0
	v_mov_b32_e32 v116, v0
	v_mov_b32_e32 v117, v0
	v_mov_b32_e32 v126, v0
	v_mov_b32_e32 v127, v0
	v_mov_b32_e32 v128, v0
	v_mov_b32_e32 v129, v0
	v_mov_b32_e32 v130, v0
	v_mov_b32_e32 v131, v0
	v_mov_b32_e32 v132, v0
	v_mov_b32_e32 v133, v0

; template <class Epi, class Sched, bool ALIGN_EPI = false, bool SP2 = false>
; __device__ __forceinline__ void gemm_phase(PG8_LAS unsigned char* lds, const Gemm g, const Sched& S, const Epi& E, const int tid) {
;     ...
;         const bool has_next = S.next(ui + 1, nxt);
;         const char* nA = has_next ? (const char*)g.A + (size_t)nxt.pm * tstep : cA; const char* nB = has_next ? (const char*)g.Bt + (size_t)nxt.pn * tstep : cB;
.LBB0_398:
	v_cndmask_b32_e64 v0, 0, 1, s[44:45]
	v_cmp_ne_u32_e64 s[46:47], 1, v0
	s_andn2_b64 vcc, exec, s[44:45]
	s_add_u32 s44, s50, 0x2b00
	s_addc_u32 s45, s51, 0
	s_cbranch_vccnz .LBB0_400
	s_mul_i32 s44, s69, 0x2c0000
	s_mul_hi_i32 s45, s69, 0x2c0000
	s_add_u32 s44, s36, s44
	s_addc_u32 s45, s38, s45
.LBB0_400:
	s_and_b64 vcc, exec, s[46:47]
	s_add_u32 s46, s52, 0x2b00
	s_addc_u32 s47, s53, 0
	s_cbranch_vccnz .LBB0_402
	s_mul_i32 s46, s68, 0x2c0000
	s_mul_hi_i32 s47, s68, 0x2c0000
	s_add_u32 s46, s39, s46
	s_addc_u32 s47, s58, s47

; template <class Epi, class Sched, bool ALIGN_EPI = false, bool SP2 = false>
; __device__ __forceinline__ void gemm_phase(PG8_LAS unsigned char* lds, const Gemm g, const Sched& S, const Epi& E, const int tid) {
;     ...
;         const bool has_next = S.next(ui + 1, nxt);
;         const char* nA = has_next ? (const char*)g.A + (size_t)nxt.pm * tstep : cA; const char* nB = has_next ? (const char*)g.Bt + (size_t)nxt.pn * tstep : cB;
;     ...
; #pragma unroll
;         for (int a = 0; a < 2; ++a)
; #pragma unroll
;             for (int b = 0; b < 2; ++b)
; #pragma unroll
;                 for (int m = 0; m < 4; ++m)
; #pragma unroll
;                     for (int n = 0; n < 2; ++n) acc[a][b][m][n] = (f32x4){0.f, 0.f, 0.f, 0.f};
.LBB0_487:
	s_ashr_i32 s53, s52, 31
	s_lshl_b64 s[54:55], s[52:53], 20
	s_add_u32 s54, s2, s54
	s_addc_u32 s55, s36, s55
	s_and_b64 s[56:57], s[40:41], exec
	s_cselect_b32 s53, s55, s59
	s_cselect_b32 s72, s54, s58
	s_ashr_i32 s51, s50, 31
	s_lshl_b64 s[56:57], s[50:51], 20
	s_add_u32 s56, s38, s56
	s_addc_u32 s57, s39, s57
	s_and_b64 s[60:61], s[40:41], exec
	s_cselect_b32 s51, s57, s43
	s_cselect_b32 s73, s56, s42
	s_cselect_b32 s100, 0, 0xf00
	s_add_u32 s72, s72, s100
	s_addc_u32 s53, s53, 0
	s_add_u32 s73, s73, s100
	s_addc_u32 s51, s51, 0
	s_add_u32 s75, s42, 0x100
	s_addc_u32 s76, s43, 0
	s_add_u32 s42, s58, 0x80080
	v_mov_b32_e32 v0, 0
	s_addc_u32 s43, s59, 0
	s_mov_b32 s77, -2
	v_mov_b32_e32 v1, v0
	v_mov_b32_e32 v2, v0
	v_mov_b32_e32 v3, v0
	v_mov_b32_e32 v12, v0
	v_mov_b32_e32 v13, v0
	v_mov_b32_e32 v14, v0
	v_mov_b32_e32 v15, v0
	v_mov_b32_e32 v16, v0
	v_mov_b32_e32 v17, v0
	v_mov_b32_e32 v18, v0
	v_mov_b32_e32 v19, v0
	v_mov_b32_e32 v28, v0
	v_mov_b32_e32 v29, v0
	v_mov_b32_e32 v30, v0
	v_mov_b32_e32 v31, v0
	v_mov_b32_e32 v32, v0
	v_mov_b32_e32 v33, v0
	v_mov_b32_e32 v34, v0
	v_mov_b32_e32 v35, v0
	v_mov_b32_e32 v44, v0
	v_mov_b32_e32 v45, v0
	v_mov_b32_e32 v46, v0
	v_mov_b32_e32 v47, v0
	v_mov_b32_e32 v48, v0
	v_mov_b32_e32 v49, v0
	v_mov_b32_e32 v50, v0
	v_mov_b32_e32 v51, v0
	v_mov_b32_e32 v60, v0
	v_mov_b32_e32 v61, v0
	v_mov_b32_e32 v62, v0
	v_mov_b32_e32 v63, v0
	v_mov_b32_e32 v4, v0
	v_mov_b32_e32 v5, v0
	v_mov_b32_e32 v6, v0
	v_mov_b32_e32 v7, v0
	v_mov_b32_e32 v8, v0
	v_mov_b32_e32 v9, v0
	v_mov_b32_e32 v10, v0
	v_mov_b32_e32 v11, v0
	v_mov_b32_e32 v20, v0
	v_mov_b32_e32 v21, v0
	v_mov_b32_e32 v22, v0
	v_mov_b32_e32 v23, v0
	v_mov_b32_e32 v24, v0
	v_mov_b32_e32 v25, v0
	v_mov_b32_e32 v26, v0
	v_mov_b32_e32 v27, v0
	v_mov_b32_e32 v36, v0
	v_mov_b32_e32 v37, v0
	v_mov_b32_e32 v38, v0
	v_mov_b32_e32 v39, v0
	v_mov_b32_e32 v40, v0
	v_mov_b32_e32 v41, v0
	v_mov_b32_e32 v42, v0
	v_mov_b32_e32 v43, v0
	v_mov_b32_e32 v52, v0
	v_mov_b32_e32 v53, v0
	v_mov_b32_e32 v54, v0
	v_mov_b32_e32 v55, v0
	v_mov_b32_e32 v56, v0
	v_mov_b32_e32 v57, v0
	v_mov_b32_e32 v58, v0
	v_mov_b32_e32 v59, v0
	v_mov_b32_e32 v64, v0
	v_mov_b32_e32 v65, v0
	v_mov_b32_e32 v66, v0
	v_mov_b32_e32 v67, v0
	v_mov_b32_e32 v76, v0
	v_mov_b32_e32 v77, v0
	v_mov_b32_e32 v78, v0
	v_mov_b32_e32 v79, v0
	v_mov_b32_e32 v80, v0
	v_mov_b32_e32 v81, v0
	v_mov_b32_e32 v82, v0
	v_mov_b32_e32 v83, v0
	v_mov_b32_e32 v92, v0
	v_mov_b32_e32 v93, v0
	v_mov_b32_e32 v94, v0
	v_mov_b32_e32 v95, v0
	v_mov_b32_e32 v102, v0
	v_mov_b32_e32 v103, v0
	v_mov_b32_e32 v104, v0
	v_mov_b32_e32 v105, v0
	v_mov_b32_e32 v114, v0
	v_mov_b32_e32 v115, v0
	v_mov_b32_e32 v116, v0
	v_mov_b32_e32 v117, v0
	v_mov_b32_e32 v126, v0
	v_mov_b32_e32 v127, v0
	v_mov_b32_e32 v128, v0
	v_mov_b32_e32 v129, v0
	v_mov_b32_e32 v130, v0
	v_mov_b32_e32 v131, v0
	v_mov_b32_e32 v132, v0
	v_mov_b32_e32 v133, v0
	v_mov_b32_e32 v68, v0
	v_mov_b32_e32 v69, v0
	v_mov_b32_e32 v70, v0
	v_mov_b32_e32 v71, v0
	v_mov_b32_e32 v72, v0
	v_mov_b32_e32 v73, v0
	v_mov_b32_e32 v74, v0
	v_mov_b32_e32 v75, v0
	v_mov_b32_e32 v84, v0
	v_mov_b32_e32 v85, v0
	v_mov_b32_e32 v86, v0
	v_mov_b32_e32 v87, v0
	v_mov_b32_e32 v88, v0
	v_mov_b32_e32 v89, v0
	v_mov_b32_e32 v90, v0
	v_mov_b32_e32 v91, v0
	v_mov_b32_e32 v106, v0
	v_mov_b32_e32 v107, v0
	v_mov_b32_e32 v108, v0
	v_mov_b32_e32 v109, v0
	v_mov_b32_e32 v110, v0
	v_mov_b32_e32 v111, v0
	v_mov_b32_e32 v112, v0
	v_mov_b32_e32 v113, v0
	v_mov_b32_e32 v118, v0
	v_mov_b32_e32 v119, v0
	v_mov_b32_e32 v120, v0
	v_mov_b32_e32 v121, v0
	v_mov_b32_e32 v122, v0
	v_mov_b32_e32 v123, v0
	v_mov_b32_e32 v124, v0
	v_mov_b32_e32 v125, v0

; template <class Epi, class Sched, bool ALIGN_EPI = false, bool SP2 = false>
; __device__ __forceinline__ void gemm_phase(PG8_LAS unsigned char* lds, const Gemm g, const Sched& S, const Epi& E, const int tid) {
;     ...
;         const bool has_next = S.next(ui + 1, nxt);
;         const char* nA = has_next ? (const char*)g.A + (size_t)nxt.pm * tstep : cA; const char* nB = has_next ? (const char*)g.Bt + (size_t)nxt.pn * tstep : cB;
;     ...
; #pragma unroll
;         for (int a = 0; a < 2; ++a)
; #pragma unroll
;             for (int b = 0; b < 2; ++b)
; #pragma unroll
;                 for (int m = 0; m < 4; ++m)
; #pragma unroll
;                     for (int n = 0; n < 2; ++n) acc[a][b][m][n] = (f32x4){0.f, 0.f, 0.f, 0.f};
.LBB0_1198:
	s_ashr_i32 s49, s48, 31
	v_cmp_lt_i64_e32 vcc, s[50:51], v[244:245]
	s_lshl_b64 s[50:51], s[48:49], 20
	s_add_u32 s50, s36, s50
	s_addc_u32 s51, s38, s51
	s_and_b64 s[52:53], vcc, exec
	s_cselect_b32 s49, s51, s57
	s_cselect_b32 s71, s50, s56
	s_ashr_i32 s47, s46, 31
	s_lshl_b64 s[52:53], s[46:47], 20
	s_add_u32 s52, s39, s52
	s_addc_u32 s53, s60, s53
	s_and_b64 s[58:59], vcc, exec
	s_cselect_b32 s47, s53, s55
	s_cselect_b32 s72, s52, s54
	s_cselect_b32 s100, 0, 0xf00
	s_add_u32 s71, s71, s100
	s_addc_u32 s49, s49, 0
	s_add_u32 s72, s72, s100
	s_addc_u32 s47, s47, 0
	s_add_u32 s73, s54, 0x100
	s_addc_u32 s75, s55, 0
	s_add_u32 s54, s56, 0x80080
	v_mov_b32_e32 v0, 0
	s_addc_u32 s55, s57, 0
	s_mov_b32 s76, -2
	s_waitcnt lgkmcnt(0)
	v_mov_b32_e32 v1, v0
	v_mov_b32_e32 v2, v0
	v_mov_b32_e32 v3, v0
	v_mov_b32_e32 v4, v0
	v_mov_b32_e32 v5, v0
	v_mov_b32_e32 v6, v0
	v_mov_b32_e32 v7, v0
	v_mov_b32_e32 v16, v0
	v_mov_b32_e32 v17, v0
	v_mov_b32_e32 v18, v0
	v_mov_b32_e32 v19, v0
	v_mov_b32_e32 v20, v0
	v_mov_b32_e32 v21, v0
	v_mov_b32_e32 v22, v0
	v_mov_b32_e32 v23, v0
	v_mov_b32_e32 v32, v0
	v_mov_b32_e32 v33, v0
	v_mov_b32_e32 v34, v0
	v_mov_b32_e32 v35, v0
	v_mov_b32_e32 v36, v0
	v_mov_b32_e32 v37, v0
	v_mov_b32_e32 v38, v0
	v_mov_b32_e32 v39, v0
	v_mov_b32_e32 v48, v0
	v_mov_b32_e32 v49, v0
	v_mov_b32_e32 v50, v0
	v_mov_b32_e32 v51, v0
	v_mov_b32_e32 v52, v0
	v_mov_b32_e32 v53, v0
	v_mov_b32_e32 v54, v0
	v_mov_b32_e32 v55, v0
	v_mov_b32_e32 v8, v0
	v_mov_b32_e32 v9, v0
	v_mov_b32_e32 v10, v0
	v_mov_b32_e32 v11, v0
	v_mov_b32_e32 v12, v0
	v_mov_b32_e32 v13, v0
	v_mov_b32_e32 v14, v0
	v_mov_b32_e32 v15, v0
	v_mov_b32_e32 v24, v0
	v_mov_b32_e32 v25, v0
	v_mov_b32_e32 v26, v0
	v_mov_b32_e32 v27, v0
	v_mov_b32_e32 v28, v0
	v_mov_b32_e32 v29, v0
	v_mov_b32_e32 v30, v0
	v_mov_b32_e32 v31, v0
	v_mov_b32_e32 v40, v0
	v_mov_b32_e32 v41, v0
	v_mov_b32_e32 v42, v0
	v_mov_b32_e32 v43, v0
	v_mov_b32_e32 v44, v0
	v_mov_b32_e32 v45, v0
	v_mov_b32_e32 v46, v0
	v_mov_b32_e32 v47, v0
	v_mov_b32_e32 v56, v0
	v_mov_b32_e32 v57, v0
	v_mov_b32_e32 v58, v0
	v_mov_b32_e32 v59, v0
	v_mov_b32_e32 v60, v0
	v_mov_b32_e32 v61, v0
	v_mov_b32_e32 v62, v0
	v_mov_b32_e32 v63, v0
	v_mov_b32_e32 v64, v0
	v_mov_b32_e32 v65, v0
	v_mov_b32_e32 v66, v0
	v_mov_b32_e32 v67, v0
	v_mov_b32_e32 v68, v0
	v_mov_b32_e32 v69, v0
	v_mov_b32_e32 v70, v0
	v_mov_b32_e32 v71, v0
	v_mov_b32_e32 v80, v0
	v_mov_b32_e32 v81, v0
	v_mov_b32_e32 v82, v0
	v_mov_b32_e32 v83, v0
	v_mov_b32_e32 v84, v0
	v_mov_b32_e32 v85, v0
	v_mov_b32_e32 v86, v0
	v_mov_b32_e32 v87, v0
	v_mov_b32_e32 v102, v0
	v_mov_b32_e32 v103, v0
	v_mov_b32_e32 v104, v0
	v_mov_b32_e32 v105, v0
	v_mov_b32_e32 v106, v0
	v_mov_b32_e32 v107, v0
	v_mov_b32_e32 v108, v0
	v_mov_b32_e32 v109, v0
	v_mov_b32_e32 v118, v0
	v_mov_b32_e32 v119, v0
	v_mov_b32_e32 v120, v0
	v_mov_b32_e32 v121, v0
	v_mov_b32_e32 v122, v0
	v_mov_b32_e32 v123, v0
	v_mov_b32_e32 v124, v0
	v_mov_b32_e32 v125, v0
	v_mov_b32_e32 v72, v0
	v_mov_b32_e32 v73, v0
	v_mov_b32_e32 v74, v0
	v_mov_b32_e32 v75, v0
	v_mov_b32_e32 v76, v0
	v_mov_b32_e32 v77, v0
	v_mov_b32_e32 v78, v0
	v_mov_b32_e32 v79, v0
	v_mov_b32_e32 v88, v0
	v_mov_b32_e32 v89, v0
	v_mov_b32_e32 v90, v0
	v_mov_b32_e32 v91, v0
	v_mov_b32_e32 v92, v0
	v_mov_b32_e32 v93, v0
	v_mov_b32_e32 v94, v0
	v_mov_b32_e32 v95, v0
	v_mov_b32_e32 v110, v0
	v_mov_b32_e32 v111, v0
	v_mov_b32_e32 v112, v0
	v_mov_b32_e32 v113, v0
	v_mov_b32_e32 v114, v0
	v_mov_b32_e32 v115, v0
	v_mov_b32_e32 v116, v0
	v_mov_b32_e32 v117, v0
	v_mov_b32_e32 v134, v0
	v_mov_b32_e32 v135, v0
	v_mov_b32_e32 v136, v0
	v_mov_b32_e32 v137, v0
	v_mov_b32_e32 v138, v0
	v_mov_b32_e32 v139, v0
	v_mov_b32_e32 v140, v0
	v_mov_b32_e32 v141, v0
